# deterministic meta-row sumsq (partials + fixed-order sum instead of float atomic), on top of previous stack
# speedup vs baseline: 1.0166x; 1.0027x over previous
.LBB0_338:
	v_add_u32_e32 v9, s10, v6
	v_mad_i64_i32 v[22:23], s[18:19], v9, s31, v[2:3]
	global_load_dwordx4 v[64:67], v[0:1], off
	global_load_dwordx4 v[152:155], v[22:23], off
	global_load_dwordx4 v[68:71], v[0:1], off offset:64
	global_load_dwordx4 v[156:159], v[22:23], off offset:64
	global_load_dwordx4 v[72:75], v[0:1], off offset:128
	global_load_dwordx4 v[160:163], v[22:23], off offset:128
	global_load_dwordx4 v[76:79], v[0:1], off offset:192
	global_load_dwordx4 v[164:167], v[22:23], off offset:192
	global_load_dwordx4 v[80:83], v[0:1], off offset:256
	global_load_dwordx4 v[168:171], v[22:23], off offset:256
	global_load_dwordx4 v[84:87], v[0:1], off offset:320
	global_load_dwordx4 v[172:175], v[22:23], off offset:320
	global_load_dwordx4 v[88:91], v[0:1], off offset:384
	global_load_dwordx4 v[176:179], v[22:23], off offset:384
	global_load_dwordx4 v[92:95], v[0:1], off offset:448
	global_load_dwordx4 v[180:183], v[22:23], off offset:448
	global_load_dwordx4 v[96:99], v[0:1], off offset:512
	global_load_dwordx4 v[184:187], v[22:23], off offset:512
	global_load_dwordx4 v[100:103], v[0:1], off offset:576
	global_load_dwordx4 v[188:191], v[22:23], off offset:576
	global_load_dwordx4 v[104:107], v[0:1], off offset:640
	global_load_dwordx4 v[192:195], v[22:23], off offset:640
	s_andn2_b64 vcc, exec, s[4:5]
	s_waitcnt vmcnt(20)
	v_mfma_f32_16x16x32_bf16 v[10:13], v[152:155], v[64:67], 0
	s_waitcnt vmcnt(18)
	v_mfma_f32_16x16x32_bf16 v[10:13], v[156:159], v[68:71], v[10:13]
	s_waitcnt vmcnt(16)
	v_mfma_f32_16x16x32_bf16 v[10:13], v[160:163], v[72:75], v[10:13]
	s_waitcnt vmcnt(14)
	v_mfma_f32_16x16x32_bf16 v[10:13], v[164:167], v[76:79], v[10:13]
	s_waitcnt vmcnt(12)
	v_mfma_f32_16x16x32_bf16 v[10:13], v[168:171], v[80:83], v[10:13]
	s_waitcnt vmcnt(10)
	v_mfma_f32_16x16x32_bf16 v[10:13], v[172:175], v[84:87], v[10:13]
	s_waitcnt vmcnt(8)
	v_mfma_f32_16x16x32_bf16 v[10:13], v[176:179], v[88:91], v[10:13]
	s_waitcnt vmcnt(6)
	v_mfma_f32_16x16x32_bf16 v[10:13], v[180:183], v[92:95], v[10:13]
	s_waitcnt vmcnt(4)
	v_mfma_f32_16x16x32_bf16 v[10:13], v[184:187], v[96:99], v[10:13]
	s_waitcnt vmcnt(2)
	v_mfma_f32_16x16x32_bf16 v[10:13], v[188:191], v[100:103], v[10:13]
	s_waitcnt vmcnt(0)
	v_mfma_f32_16x16x32_bf16 v[10:13], v[192:195], v[104:107], v[10:13]
	s_nop 7
	ds_write_b128 v8, v[10:13]
	s_waitcnt lgkmcnt(0)
	s_barrier
	s_cbranch_vccnz .LBB0_337
	ds_read_b128 v[10:13], v7
	ds_read_b128 v[14:17], v7 offset:1024
	s_load_dwordx2 s[18:19], s[80:81], 0x8
	s_ashr_i32 s11, s10, 31
	v_lshl_add_u64 v[18:19], v[148:149], 0, s[10:11]
	v_lshlrev_b64 v[20:21], 2, v[18:19]
	s_waitcnt lgkmcnt(0)
	v_pk_add_f32 v[16:17], v[12:13], v[16:17]
	v_pk_add_f32 v[14:15], v[10:11], v[14:15]
	ds_read_b128 v[10:13], v7 offset:2048
	s_waitcnt lgkmcnt(0)
	v_pk_add_f32 v[16:17], v[16:17], v[12:13]
	v_pk_add_f32 v[14:15], v[14:15], v[10:11]
	ds_read_b128 v[10:13], v7 offset:3072
	s_waitcnt lgkmcnt(0)
	v_pk_add_f32 v[16:17], v[16:17], v[12:13]
	v_pk_add_f32 v[14:15], v[14:15], v[10:11]
	ds_read_b128 v[10:13], v7 offset:4096
	s_waitcnt lgkmcnt(0)
	v_pk_add_f32 v[16:17], v[16:17], v[12:13]
	v_pk_add_f32 v[14:15], v[14:15], v[10:11]
	ds_read_b128 v[10:13], v7 offset:5120
	s_waitcnt lgkmcnt(0)
	v_pk_add_f32 v[16:17], v[16:17], v[12:13]
	v_pk_add_f32 v[14:15], v[14:15], v[10:11]
	ds_read_b128 v[10:13], v7 offset:6144
	s_waitcnt lgkmcnt(0)
	v_pk_add_f32 v[16:17], v[16:17], v[12:13]
	v_pk_add_f32 v[14:15], v[14:15], v[10:11]
	ds_read_b128 v[10:13], v7 offset:7168
	s_waitcnt lgkmcnt(0)
	v_pk_add_f32 v[14:15], v[14:15], v[10:11]
	v_lshl_add_u64 v[10:11], s[18:19], 0, v[20:21]
	v_pk_add_f32 v[16:17], v[16:17], v[12:13]
	global_load_dwordx4 v[10:13], v[10:11], off
	s_waitcnt vmcnt(0)
	v_pk_fma_f32 v[10:11], v[14:15], 0.5, v[10:11] op_sel_hi:[1,0,1]
	v_pk_fma_f32 v[12:13], v[16:17], 0.5, v[12:13] op_sel_hi:[1,0,1]
	v_lshl_add_u64 v[14:15], s[6:7], 0, v[20:21]
	v_mul_f32_e32 v9, v11, v11
	global_store_dwordx4 v[14:15], v[10:13], off
	v_cvt_pk_bf16_f32 v14, v10, v11
	v_fmac_f32_e32 v9, v10, v10
	v_mul_f32_e32 v10, v13, v13
	v_fmac_f32_e32 v10, v12, v12
	v_and_b32_e32 v11, 64, v210
	v_add_f32_e32 v9, v9, v10
	v_xor_b32_e32 v10, 16, v210
	v_add_u32_e32 v11, 64, v11
	v_cmp_lt_i32_e32 vcc, v10, v11
	v_cvt_pk_bf16_f32 v15, v12, v13
	v_lshl_add_u64 v[16:17], v[18:19], 1, s[8:9]
	v_cndmask_b32_e32 v10, v210, v10, vcc
	v_lshlrev_b32_e32 v10, 2, v10
	ds_bpermute_b32 v10, v10, v9
	global_store_dwordx2 v[16:17], v[14:15], off
	s_waitcnt lgkmcnt(0)
	v_add_f32_e32 v9, v9, v10
	v_xor_b32_e32 v10, 32, v210
	v_cmp_lt_i32_e32 vcc, v10, v11
	s_nop 1
	v_cndmask_b32_e32 v10, v210, v10, vcc
	v_lshlrev_b32_e32 v10, 2, v10
	ds_bpermute_b32 v10, v10, v9
	s_and_saveexec_b64 s[18:19], s[0:1]
	s_cbranch_execz .LBB0_336
	s_waitcnt lgkmcnt(0)
	v_add_f32_e32 v9, v9, v10
	v_and_b32_e32 v10, 15, v210
	v_mul_u32_u24_e32 v10, 0xfc, v10
	s_lshl_b32 s21, s20, 2
	s_add_u32 s21, s21, 0xe0000
	v_add_u32_e32 v10, s21, v10
	v_mov_b32_e32 v11, 0
	v_lshl_add_u64 v[10:11], v[4:5], 0, v[10:11]
	global_store_dword v[10:11], v9, off
	s_branch .LBB0_336

.LBB0_778:
	v_lshl_add_u64 v[8:9], v[8:9], 0, v[148:149]
	v_lshl_add_u64 v[8:9], s[4:5], 1, v[8:9]
	global_load_dwordx4 v[14:17], v[0:1], off
	global_load_dwordx4 v[18:21], v[8:9], off
	s_andn2_b64 vcc, exec, s[8:9]
	s_waitcnt vmcnt(0)
	v_mfma_f32_16x16x32_bf16 v[14:17], v[18:21], v[14:17], 0
	global_load_dwordx4 v[18:21], v[0:1], off offset:64
	global_load_dwordx4 v[22:25], v[8:9], off offset:64
	s_waitcnt vmcnt(0)
	v_mfma_f32_16x16x32_bf16 v[14:17], v[22:25], v[18:21], v[14:17]
	global_load_dwordx4 v[18:21], v[0:1], off offset:128
	global_load_dwordx4 v[22:25], v[8:9], off offset:128
	s_waitcnt vmcnt(0)
	v_mfma_f32_16x16x32_bf16 v[14:17], v[22:25], v[18:21], v[14:17]
	global_load_dwordx4 v[18:21], v[0:1], off offset:192
	global_load_dwordx4 v[22:25], v[8:9], off offset:192
	s_waitcnt vmcnt(0)
	v_mfma_f32_16x16x32_bf16 v[14:17], v[22:25], v[18:21], v[14:17]
	s_nop 7
	ds_write_b128 v11, v[14:17]
	s_waitcnt lgkmcnt(0)
	s_barrier
	s_cbranch_vccnz .LBB0_773
	ds_read_b128 v[14:17], v10
	ds_read_b128 v[18:21], v10 offset:1024
	s_waitcnt lgkmcnt(0)
	v_pk_add_f32 v[8:9], v[16:17], v[20:21]
	v_pk_add_f32 v[18:19], v[14:15], v[18:19]
	ds_read_b128 v[14:17], v10 offset:2048
	s_waitcnt lgkmcnt(0)
	v_pk_add_f32 v[8:9], v[8:9], v[16:17]
	v_pk_add_f32 v[18:19], v[18:19], v[14:15]
	ds_read_b128 v[14:17], v10 offset:3072
	s_waitcnt lgkmcnt(0)
	v_pk_add_f32 v[8:9], v[8:9], v[16:17]
	v_pk_add_f32 v[18:19], v[18:19], v[14:15]
	ds_read_b128 v[14:17], v10 offset:4096
	s_waitcnt lgkmcnt(0)
	v_pk_add_f32 v[8:9], v[8:9], v[16:17]
	v_pk_add_f32 v[18:19], v[18:19], v[14:15]
	ds_read_b128 v[14:17], v10 offset:5120
	s_waitcnt lgkmcnt(0)
	v_pk_add_f32 v[8:9], v[8:9], v[16:17]
	v_pk_add_f32 v[18:19], v[18:19], v[14:15]
	ds_read_b128 v[14:17], v10 offset:6144
	s_waitcnt lgkmcnt(0)
	v_pk_add_f32 v[8:9], v[8:9], v[16:17]
	v_pk_add_f32 v[18:19], v[18:19], v[14:15]
	ds_read_b128 v[14:17], v10 offset:7168
	v_and_b32_e32 v26, 15, v210
	v_mul_u32_u24_e32 v26, 0xfc, v26
	v_add_u32_e32 v26, 0xe0000, v26
	v_mov_b32_e32 v27, 0
	v_lshl_add_u64 v[26:27], v[2:3], 0, v[26:27]
	global_load_dwordx4 v[64:67], v[26:27], off sc1
	global_load_dwordx4 v[68:71], v[26:27], off offset:16 sc1
	global_load_dwordx4 v[72:75], v[26:27], off offset:32 sc1
	global_load_dwordx4 v[76:79], v[26:27], off offset:48 sc1
	global_load_dwordx4 v[80:83], v[26:27], off offset:64 sc1
	global_load_dwordx4 v[84:87], v[26:27], off offset:80 sc1
	global_load_dwordx4 v[88:91], v[26:27], off offset:96 sc1
	global_load_dwordx4 v[92:95], v[26:27], off offset:112 sc1
	global_load_dwordx4 v[96:99], v[26:27], off offset:128 sc1
	global_load_dwordx4 v[100:103], v[26:27], off offset:144 sc1
	global_load_dwordx4 v[104:107], v[26:27], off offset:160 sc1
	global_load_dwordx4 v[108:111], v[26:27], off offset:176 sc1
	global_load_dwordx4 v[112:115], v[26:27], off offset:192 sc1
	global_load_dwordx4 v[116:119], v[26:27], off offset:208 sc1
	global_load_dwordx4 v[120:123], v[26:27], off offset:224 sc1
	global_load_dwordx4 v[124:127], v[26:27], off offset:240 sc1
	s_waitcnt lgkmcnt(0)
	v_pk_add_f32 v[14:15], v[18:19], v[14:15]
	v_pk_add_f32 v[8:9], v[8:9], v[16:17]
	s_waitcnt vmcnt(0)
	v_add_f32_e32 v64, v64, v65
	v_add_f32_e32 v66, v66, v67
	v_add_f32_e32 v64, v64, v66
	v_add_f32_e32 v68, v68, v69
	v_add_f32_e32 v70, v70, v71
	v_add_f32_e32 v68, v68, v70
	v_add_f32_e32 v72, v72, v73
	v_add_f32_e32 v74, v74, v75
	v_add_f32_e32 v72, v72, v74
	v_add_f32_e32 v76, v76, v77
	v_add_f32_e32 v78, v78, v79
	v_add_f32_e32 v76, v76, v78
	v_add_f32_e32 v80, v80, v81
	v_add_f32_e32 v82, v82, v83
	v_add_f32_e32 v80, v80, v82
	v_add_f32_e32 v84, v84, v85
	v_add_f32_e32 v86, v86, v87
	v_add_f32_e32 v84, v84, v86
	v_add_f32_e32 v88, v88, v89
	v_add_f32_e32 v90, v90, v91
	v_add_f32_e32 v88, v88, v90
	v_add_f32_e32 v92, v92, v93
	v_add_f32_e32 v94, v94, v95
	v_add_f32_e32 v92, v92, v94
	v_add_f32_e32 v96, v96, v97
	v_add_f32_e32 v98, v98, v99
	v_add_f32_e32 v96, v96, v98
	v_add_f32_e32 v100, v100, v101
	v_add_f32_e32 v102, v102, v103
	v_add_f32_e32 v100, v100, v102
	v_add_f32_e32 v104, v104, v105
	v_add_f32_e32 v106, v106, v107
	v_add_f32_e32 v104, v104, v106
	v_add_f32_e32 v108, v108, v109
	v_add_f32_e32 v110, v110, v111
	v_add_f32_e32 v108, v108, v110
	v_add_f32_e32 v112, v112, v113
	v_add_f32_e32 v114, v114, v115
	v_add_f32_e32 v112, v112, v114
	v_add_f32_e32 v116, v116, v117
	v_add_f32_e32 v118, v118, v119
	v_add_f32_e32 v116, v116, v118
	v_add_f32_e32 v120, v120, v121
	v_add_f32_e32 v122, v122, v123
	v_add_f32_e32 v120, v120, v122
	v_add_f32_e32 v124, v124, v125
	v_add_f32_e32 v126, v126, v127
	v_add_f32_e32 v124, v124, v126
	v_add_f32_e32 v64, v64, v68
	v_add_f32_e32 v72, v72, v76
	v_add_f32_e32 v80, v80, v84
	v_add_f32_e32 v88, v88, v92
	v_add_f32_e32 v96, v96, v100
	v_add_f32_e32 v104, v104, v108
	v_add_f32_e32 v112, v112, v116
	v_add_f32_e32 v120, v120, v124
	v_add_f32_e32 v64, v64, v72
	v_add_f32_e32 v80, v80, v88
	v_add_f32_e32 v96, v96, v104
	v_add_f32_e32 v112, v112, v120
	v_add_f32_e32 v64, v64, v80
	v_add_f32_e32 v96, v96, v112
	v_add_f32_e32 v64, v64, v96
	v_mov_b32_e32 v7, v64
	v_fmamk_f32 v7, v7, 0x3a800000, v207
	v_rsq_f32_e32 v18, v7
	s_nop 0
	v_pk_mul_f32 v[16:17], v[8:9], v[18:19] op_sel_hi:[1,0]
	v_lshl_add_u64 v[8:9], v[4:5], 0, s[48:49]
	v_pk_mul_f32 v[14:15], v[14:15], v[18:19] op_sel_hi:[1,0]
	v_lshl_add_u64 v[18:19], v[8:9], 2, s[12:13]
	global_store_dwordx4 v[18:19], v[14:17], off
	v_lshl_add_u64 v[8:9], v[8:9], 1, s[2:3]
	s_nop 0
	v_cvt_pk_bf16_f32 v14, v14, v15
	v_cvt_pk_bf16_f32 v15, v16, v17
	global_store_dwordx2 v[8:9], v[14:15], off
	s_branch .LBB0_773
